# walks: wait for next-step loads moved from end of step to just after the next step's first barrier (register copies moved along, pre-loop copies added)
# speedup vs baseline: 1.0157x; 1.0089x over previous
.LBB0_443:
	v_mov_b32_e32 v33, v1
	v_lshl_add_u64 v[2:3], v[2:3], 1, v[40:41]
	v_lshl_add_u64 v[40:41], s[68:69], 0, v[32:33]
	v_lshl_add_u64 v[32:33], s[70:71], 0, v[0:1]
	s_movk_i32 s10, 0xffbe
	v_lshl_add_u64 v[32:33], v[46:47], 1, v[32:33]
	v_mov_b32_e32 v49, v1
	v_mul_lo_u32 v0, v186, s10
	s_movk_i32 s10, 0x840
	v_mul_u32_u24_e32 v55, 0x84, v42
	v_add_u32_e32 v56, 0x41, v84
	v_lshl_add_u64 v[42:43], v[34:35], 1, v[68:69]
	v_lshl_add_u64 v[44:45], v[44:45], 1, s[84:85]
	v_lshl_add_u64 v[46:47], v[32:33], 0, v[48:49]
	v_mul_lo_u32 v57, v186, s10
	s_mov_b64 s[10:11], 0
	s_waitcnt vmcnt(0)
	v_mov_b64_e32 v[48:49], v[28:29]
	v_mov_b64_e32 v[50:51], v[30:31]
	s_branch .LBB0_445
.LBB0_444:
	s_or_b64 exec, exec, s[14:15]
	s_setprio 0
	v_add_u32_e32 v0, -1, v0
	v_mov_b32_e32 v84, v83
	s_andn2_b64 exec, exec, s[10:11]
	s_cbranch_execz .LBB0_474
.LBB0_445:
	v_cmp_lt_i32_e32 vcc, 3, v84
	s_nop 1
	v_cndmask_b32_e32 v32, 3, v217, vcc
	v_add_u32_e32 v32, v32, v0
	v_cndmask_b32_e64 v32, v32, v84, s[60:61]
	v_add_u32_e32 v32, v32, v55
	v_mul_hi_i32 v33, v32, s7
	v_lshrrev_b32_e32 v34, 31, v33
	v_ashrrev_i32_e32 v33, 5, v33
	v_add_u32_e32 v33, v33, v34
	v_mul_lo_u32 v34, v33, s17
	v_sub_u32_e32 v32, v32, v34
	v_cmp_lt_i32_e32 vcc, 3, v32
	v_lshlrev_b32_e32 v34, 6, v32
	s_and_saveexec_b64 s[14:15], vcc
	s_xor_b64 s[14:15], exec, s[14:15]
	v_lshlrev_b32_e32 v32, 13, v33
	s_movk_i32 s18, 0xff00
	v_add3_u32 v32, v34, v32, s18
	s_andn2_saveexec_b64 s[14:15], s[14:15]
	v_lshlrev_b32_e32 v32, 8, v33
	s_mov_b32 s18, 0x8000
	v_add3_u32 v32, v32, v34, s18
	s_or_b64 exec, exec, s[14:15]
	s_waitcnt lgkmcnt(0)
	s_barrier
	s_and_b64 vcc, exec, s[62:63]
	s_cbranch_vccnz .Lgla_wait_all
	s_waitcnt vmcnt(2)
	s_branch .Lgla_wait_done

.Lgla_wait_done:
	v_mov_b64_e32 v[28:29], v[48:49]
	v_mov_b64_e32 v[30:31], v[50:51]
	s_and_b64 vcc, exec, s[2:3]
	s_cbranch_vccz .LBB0_451
	s_and_b64 s[14:15], s[26:27], exec
	s_cbranch_execz .LBB0_452
	s_branch .LBB0_453

.LBB0_511:
	v_or_b32_e32 v98, v46, v83
	s_movk_i32 s10, 0xffd4
	v_lshlrev_b32_e32 v46, 4, v98
	v_mov_b32_e32 v47, v1
	v_mul_lo_u32 v194, v186, s10
	s_movk_i32 s10, 0x580
	v_mul_u32_u24_e32 v192, 0x84, v53
	s_mov_b32 s18, 44
	v_add_u32_e32 v193, 44, v52
	v_mov_b32_e32 v99, v1
	v_lshl_add_u64 v[100:101], v[48:49], 1, v[50:51]
	v_lshl_add_u64 v[102:103], s[90:91], 0, v[46:47]
	v_mul_lo_u32 v195, v186, s10
	v_mov_b32_e32 v57, 0
	s_waitcnt vmcnt(0)
	v_mov_b32_e32 v91, v96
	v_mov_b64_e32 v[108:109], v[104:105]
	v_mov_b64_e32 v[110:111], v[106:107]
.LBB0_512:
	v_cmp_lt_i32_e32 vcc, 3, v52
	s_nop 1
	v_cndmask_b32_e32 v46, 3, v217, vcc
	v_add3_u32 v46, v194, v46, s18
	v_subrev_u32_e32 v46, 44, v46
	v_cndmask_b32_e64 v46, v46, v52, s[62:63]
	v_add_u32_e32 v47, v46, v192
	v_mul_hi_i32 v46, v47, s7
	v_lshrrev_b32_e32 v48, 31, v46
	v_ashrrev_i32_e32 v46, 5, v46
	v_add_u32_e32 v46, v46, v48
	v_mul_lo_u32 v48, v46, s17
	v_sub_u32_e32 v47, v47, v48
	v_cmp_lt_i32_e32 vcc, 3, v47
	v_lshlrev_b32_e32 v47, 6, v47
	s_and_saveexec_b64 s[10:11], vcc
	s_xor_b64 s[10:11], exec, s[10:11]
	v_lshlrev_b32_e32 v46, 13, v46
	s_movk_i32 s14, 0xff00
	v_add3_u32 v97, v47, v46, s14
	s_andn2_saveexec_b64 s[10:11], s[10:11]
	v_lshlrev_b32_e32 v46, 8, v46
	s_mov_b32 s14, 0x8000
	v_add3_u32 v97, v46, v47, s14
	s_or_b64 exec, exec, s[10:11]
	s_waitcnt lgkmcnt(0)
	s_barrier
	s_and_b64 vcc, exec, s[60:61]
	s_cbranch_vccnz .Lml_wait_all
	s_waitcnt vmcnt(2)
	s_branch .Lml_wait_done

.Lml_wait_done:
	v_mov_b32_e32 v96, v91
	v_mov_b64_e32 v[104:105], v[108:109]
	v_mov_b64_e32 v[106:107], v[110:111]
	s_and_b64 vcc, exec, s[60:61]
	s_mov_b64 s[10:11], -1
	s_cbranch_vccz .LBB0_550
	s_andn2_b64 vcc, exec, s[10:11]
	s_cbranch_vccz .LBB0_551

.LBB0_554:
	v_mov_b32_e32 v52, v196
	s_branch .LBB0_512
